# grid barrier: non-leader workgroups wait on the chip-wide generation word directly (one relay hop less)
# speedup vs baseline: 1.0090x; 1.0090x over previous
.LBB0_873:
	s_or_b64 exec, exec, s[2:3]
	v_cvt_f32_u32_e32 v5, v3
	s_waitcnt vmcnt(0)
	v_readfirstlane_b32 s2, v4
	v_sub_u32_e32 v4, 0, v3
	v_rcp_iflag_f32_e32 v5, v5
	v_add_u32_e32 v6, s2, v1
	v_mul_f32_e32 v5, 0x4f7ffffe, v5
	v_cvt_u32_f32_e32 v5, v5
	v_mul_lo_u32 v1, v4, v5
	v_mul_hi_u32 v1, v5, v1
	v_add_u32_e32 v1, v5, v1
	v_mul_hi_u32 v1, v6, v1
	v_mul_lo_u32 v4, v1, v3
	v_sub_u32_e32 v4, v6, v4
	v_add_u32_e32 v5, 1, v1
	v_cmp_ge_u32_e32 vcc, v4, v3
	s_nop 1
	v_cndmask_b32_e32 v1, v1, v5, vcc
	v_sub_u32_e32 v5, v4, v3
	v_cndmask_b32_e32 v4, v4, v5, vcc
	v_add_u32_e32 v5, 1, v1
	v_cmp_ge_u32_e32 vcc, v4, v3
	v_add_u32_e32 v4, 1, v6
	s_nop 0
	v_cndmask_b32_e32 v1, v1, v5, vcc
	v_mul_lo_u32 v5, v3, v1
	v_add_u32_e32 v3, v5, v3
	v_cmp_ne_u32_e32 vcc, v4, v3
	s_and_saveexec_b64 s[2:3], vcc
	s_xor_b64 s[2:3], exec, s[2:3]
	s_cbranch_execz .LBB0_887
	v_readlane_b32 s4, v254, 36
	v_readlane_b32 s5, v254, 37
	s_waitcnt lgkmcnt(0)
	s_nop 3
	global_load_dword v0, v2, s[4:5] sc1
	s_waitcnt vmcnt(0)
	v_cmp_eq_u32_e32 vcc, v0, v1
	s_and_saveexec_b64 s[4:5], vcc
	s_cbranch_execz .LBB0_886
	s_mov_b32 s16, 1
	s_mov_b64 s[6:7], 0
	s_branch .LBB0_877

.LBB0_879:
	v_readlane_b32 s10, v254, 36
	v_readlane_b32 s11, v254, 37
	s_add_i32 s16, s16, 1
	s_mov_b64 s[12:13], -1
	s_nop 2
	global_load_dword v0, v2, s[10:11] sc1
	s_waitcnt vmcnt(0)
	v_cmp_ne_u32_e32 vcc, v0, v1
	s_orn2_b64 s[10:11], vcc, exec
	s_branch .LBB0_876
